# v35 + MLA QK: the two refill ds_reads of each same-accumulator MFMA pair issued right after the pair
# speedup vs baseline: 1.0086x; 1.0086x over previous
.LBB0_2904:
	v_add_u32_e32 v0, s28, v183
	ds_read_b128 v[2:5], v0 offset:24576
	ds_read_b128 v[6:9], v0 offset:28672
	ds_read_b128 v[10:13], v0 offset:32768
	ds_read_b128 v[184:187], v0 offset:36864
	v_exp_f32_e32 v14, v96
	v_exp_f32_e32 v190, v97
	v_exp_f32_e32 v98, v98
	v_exp_f32_e32 v192, v99
	v_exp_f32_e32 v15, v100
	v_exp_f32_e32 v191, v101
	v_exp_f32_e32 v99, v102
	v_exp_f32_e32 v193, v103
	v_add_u32_e32 v0, s28, v182
	v_pk_add_f32 v[96:97], v[14:15], v[190:191]
	v_pk_add_f32 v[100:101], v[98:99], v[192:193]
	s_nop 0
	v_pk_add_f32 v[96:97], v[96:97], v[100:101]
	v_cvt_pk_bf16_f32 v99, v99, v193
	v_pk_add_f32 v[202:203], v[96:97], v[96:97] op_sel_hi:[0,1]
	v_cvt_pk_bf16_f32 v96, v14, v190
	v_cvt_pk_bf16_f32 v97, v98, v192
	v_cvt_pk_bf16_f32 v98, v15, v191
	ds_read_b128 v[100:103], v0 offset:24576
	ds_read_b128 v[190:193], v0 offset:28672
	ds_read_b128 v[194:197], v0 offset:32768
	ds_read_b128 v[198:201], v0 offset:36864
	s_waitcnt lgkmcnt(0)
	v_mfma_f32_32x32x16_bf16 v[64:79], v[2:5], v[96:99], v[64:79]
	v_mfma_f32_32x32x16_bf16 v[48:63], v[6:9], v[96:99], v[48:63]
	v_mfma_f32_32x32x16_bf16 v[32:47], v[10:13], v[96:99], v[32:47]
	v_mfma_f32_32x32x16_bf16 v[16:31], v[184:187], v[96:99], v[16:31]
	v_exp_f32_e32 v2, v104
	v_exp_f32_e32 v4, v105
	v_exp_f32_e32 v3, v106
	v_exp_f32_e32 v5, v107
	v_exp_f32_e32 v6, v108
	v_exp_f32_e32 v8, v109
	v_exp_f32_e32 v7, v110
	v_exp_f32_e32 v9, v111
	v_pk_add_f32 v[10:11], v[2:3], v[4:5]
	v_add_u32_e32 v0, s28, v180
	v_pk_add_f32 v[14:15], v[10:11], v[10:11] op_sel_hi:[0,1]
	v_pk_add_f32 v[10:11], v[6:7], v[8:9]
	v_cvt_pk_bf16_f32 v2, v2, v4
	v_pk_add_f32 v[184:185], v[10:11], v[10:11] op_sel_hi:[0,1]
	v_cvt_pk_bf16_f32 v3, v3, v5
	v_cvt_pk_bf16_f32 v4, v6, v8
	v_cvt_pk_bf16_f32 v5, v7, v9
	ds_read_b128 v[6:9], v0 offset:24576
	ds_read_b128 v[10:13], v0 offset:28672
	ds_read_b128 v[96:99], v0 offset:32768
	ds_read_b128 v[104:107], v0 offset:36864
	v_mfma_f32_32x32x16_bf16 v[64:79], v[100:103], v[2:5], v[64:79]
	v_mfma_f32_32x32x16_bf16 v[48:63], v[190:193], v[2:5], v[48:63]
	v_mfma_f32_32x32x16_bf16 v[32:47], v[194:197], v[2:5], v[32:47]
	v_mfma_f32_32x32x16_bf16 v[16:31], v[198:201], v[2:5], v[16:31]
	v_exp_f32_e32 v0, v80
	v_exp_f32_e32 v2, v81
	v_exp_f32_e32 v3, v82
	v_exp_f32_e32 v4, v83
	v_exp_f32_e32 v5, v84
	v_exp_f32_e32 v14, v85
	v_exp_f32_e32 v80, v86
	v_exp_f32_e32 v81, v87
	v_add_f32_e32 v187, v0, v2
	v_cvt_pk_bf16_f32 v2, v0, v2
	v_add_u32_e32 v0, s28, v175
	v_add_f32_e32 v191, v3, v4
	v_add_f32_e32 v193, v5, v14
	v_add_f32_e32 v195, v80, v81
	v_cvt_pk_bf16_f32 v3, v3, v4
	v_cvt_pk_bf16_f32 v4, v5, v14
	v_cvt_pk_bf16_f32 v5, v80, v81
	ds_read_b128 v[80:83], v0 offset:24576
	ds_read_b128 v[84:87], v0 offset:28672
	ds_read_b128 v[100:103], v0 offset:32768
	ds_read_b128 v[108:111], v0 offset:36864
	s_waitcnt lgkmcnt(0)
	v_mfma_f32_32x32x16_bf16 v[64:79], v[6:9], v[2:5], v[64:79]
	v_mfma_f32_32x32x16_bf16 v[48:63], v[10:13], v[2:5], v[48:63]
	v_mfma_f32_32x32x16_bf16 v[32:47], v[96:99], v[2:5], v[32:47]
	v_mfma_f32_32x32x16_bf16 v[16:31], v[104:107], v[2:5], v[16:31]
	v_exp_f32_e32 v186, v88
	v_exp_f32_e32 v190, v89
	v_exp_f32_e32 v192, v90
	v_exp_f32_e32 v194, v91
	v_exp_f32_e32 v14, v92
	v_exp_f32_e32 v184, v93
	v_exp_f32_e32 v202, v94
	v_exp_f32_e32 v0, v95
	v_cvt_pk_bf16_f32 v2, v186, v190
	v_cvt_pk_bf16_f32 v3, v192, v194
	v_cvt_pk_bf16_f32 v4, v14, v184
	v_cvt_pk_bf16_f32 v5, v202, v0
	s_nop 1
	v_mfma_f32_32x32x16_bf16 v[64:79], v[80:83], v[2:5], v[64:79]
	v_add_f32_e64 v6, v186, v190
	v_add_f32_e64 v7, v187, v191
	v_add_f32_e64 v8, v192, v194
	v_add_f32_e64 v9, v193, v195
	v_add_f32_e64 v10, v202, v0
	v_add_f32_e64 v11, v203, v1
	v_pk_add_f32 v[6:7], v[6:7], v[8:9]
	v_pk_add_f32 v[8:9], v[14:15], v[184:185]
	s_nop 0
	v_pk_add_f32 v[8:9], v[8:9], v[10:11]
	v_mfma_f32_32x32x16_bf16 v[48:63], v[84:87], v[2:5], v[48:63]
	v_add_f32_e64 v6, v6, v8
	v_add_f32_e64 v7, v7, v9
	v_pk_add_f32 v[6:7], v[6:7], v[6:7] op_sel:[0,1] op_sel_hi:[1,0]
	v_mfma_f32_32x32x16_bf16 v[32:47], v[100:103], v[2:5], v[32:47]
	v_mfma_f32_32x32x16_bf16 v[16:31], v[108:111], v[2:5], v[16:31]
	v_mov_b32_e32 v0, v6
	s_nop 1
	v_permlane32_swap_b32_e32 v6, v0
	v_add_f32_e32 v0, v6, v0
	v_add_f32_e32 v171, v171, v0
	v_add_u32_e32 v0, s1, v174
	v_add_u32_e32 v14, s1, v173
	v_add_u32_e32 v15, s1, v170
	ds_read_b128 v[2:5], v0
	ds_read_b128 v[6:9], v0 offset:12288
	ds_read_b128 v[10:13], v14
	ds_read_b128 v[184:187], v14 offset:12288
	v_add_u32_e32 v206, s1, v172
	ds_read_b128 v[190:193], v15
	ds_read_b128 v[194:197], v15 offset:12288
	ds_read_b128 v[198:201], v206
	ds_read_b128 v[202:205], v206 offset:12288
	v_xor_b32_e32 v80, 0x80000000, v181
	v_mov_b32_e32 v81, v80
	v_mov_b32_e32 v82, v80
	v_mov_b32_e32 v83, v80
	v_mov_b32_e32 v84, v80
	v_mov_b32_e32 v85, v80
	v_mov_b32_e32 v86, v80
	v_mov_b32_e32 v87, v80
	v_mov_b32_e32 v88, v80
	v_mov_b32_e32 v89, v80
	v_mov_b32_e32 v90, v80
	v_mov_b32_e32 v91, v80
	v_mov_b32_e32 v92, v80
	v_mov_b32_e32 v93, v80
	v_mov_b32_e32 v94, v80
	v_mov_b32_e32 v95, v80
	s_waitcnt lgkmcnt(0)
	s_nop 0
	v_mfma_f32_32x32x16_bf16 v[96:111], v[2:5], v[112:115], v[80:95]
	v_mfma_f32_32x32x16_bf16 v[96:111], v[10:13], v[116:119], v[96:111]
	ds_read_b128 v[2:5], v14 offset:12416
	ds_read_b128 v[10:13], v0 offset:12416
	v_mfma_f32_32x32x16_bf16 v[80:95], v[6:9], v[112:115], v[80:95]
	v_mfma_f32_32x32x16_bf16 v[80:95], v[184:187], v[116:119], v[80:95]
	ds_read_b128 v[6:9], v14 offset:128
	ds_read_b128 v[184:187], v0 offset:128
	v_mfma_f32_32x32x16_bf16 v[96:111], v[190:193], v[120:123], v[96:111]
	v_mfma_f32_32x32x16_bf16 v[96:111], v[198:201], v[124:127], v[96:111]
	ds_read_b128 v[190:193], v15 offset:128
	ds_read_b128 v[198:201], v206 offset:128
	v_mfma_f32_32x32x16_bf16 v[80:95], v[194:197], v[120:123], v[80:95]
	v_mfma_f32_32x32x16_bf16 v[80:95], v[202:205], v[124:127], v[80:95]
	ds_read_b128 v[194:197], v15 offset:12416
	ds_read_b128 v[202:205], v206 offset:12416
	s_waitcnt lgkmcnt(0)
	v_mfma_f32_32x32x16_bf16 v[96:111], v[184:187], v[128:131], v[96:111]
	v_mfma_f32_32x32x16_bf16 v[96:111], v[6:9], v[132:135], v[96:111]
	ds_read_b128 v[184:187], v0 offset:256
	ds_read_b128 v[6:9], v14 offset:256
	v_mfma_f32_32x32x16_bf16 v[80:95], v[10:13], v[128:131], v[80:95]
	v_mfma_f32_32x32x16_bf16 v[80:95], v[2:5], v[132:135], v[80:95]
	ds_read_b128 v[10:13], v0 offset:12544
	ds_read_b128 v[2:5], v14 offset:12544
	v_mfma_f32_32x32x16_bf16 v[96:111], v[190:193], v[136:139], v[96:111]
	v_mfma_f32_32x32x16_bf16 v[96:111], v[198:201], v[140:143], v[96:111]
	ds_read_b128 v[190:193], v15 offset:256
	ds_read_b128 v[198:201], v206 offset:256
	v_mfma_f32_32x32x16_bf16 v[80:95], v[194:197], v[136:139], v[80:95]
	v_mfma_f32_32x32x16_bf16 v[80:95], v[202:205], v[140:143], v[80:95]
	ds_read_b128 v[194:197], v15 offset:12544
	ds_read_b128 v[202:205], v206 offset:12544
	s_waitcnt lgkmcnt(0)
	v_mfma_f32_32x32x16_bf16 v[96:111], v[184:187], v[144:147], v[96:111]
	v_mfma_f32_32x32x16_bf16 v[96:111], v[6:9], v[148:151], v[96:111]
	v_mfma_f32_32x32x16_bf16 v[80:95], v[10:13], v[144:147], v[80:95]
	v_mfma_f32_32x32x16_bf16 v[80:95], v[2:5], v[148:151], v[80:95]
	v_mfma_f32_32x32x16_bf16 v[96:111], v[190:193], v[152:155], v[96:111]
	v_mfma_f32_32x32x16_bf16 v[96:111], v[198:201], v[156:159], v[96:111]
	v_mfma_f32_32x32x16_bf16 v[80:95], v[194:197], v[152:155], v[80:95]
	s_nop 10
	v_max_f32_e32 v0, v97, v97
	v_max_f32_e32 v2, v96, v96
	v_max_f32_e32 v0, v2, v0
	v_max3_f32 v0, v0, v98, v99
	v_max3_f32 v0, v0, v100, v101
	v_max3_f32 v0, v0, v102, v103
	v_max3_f32 v0, v0, v104, v105
	v_mfma_f32_32x32x16_bf16 v[80:95], v[202:205], v[156:159], v[80:95]
	v_max3_f32 v0, v0, v106, v107
	v_max3_f32 v0, v0, v108, v109
	v_max3_f32 v0, v0, v110, v111
	s_mov_b32 s28, 0x41000000
	s_nop 7
	v_max3_f32 v0, v0, v80, v81
	v_max3_f32 v0, v0, v82, v83
	v_max3_f32 v0, v0, v84, v85
	v_max3_f32 v0, v0, v86, v87
	v_max3_f32 v0, v0, v88, v89
	v_max3_f32 v0, v0, v90, v91
	v_max3_f32 v0, v0, v92, v93
	v_max3_f32 v0, v0, v94, v95
	v_mov_b32_e32 v2, v0
	s_nop 1
	v_permlane32_swap_b32_e32 v0, v2
	v_max_f32_e32 v2, v2, v2
	v_max_f32_e32 v0, v0, v0
	v_max_f32_e32 v0, v0, v2
	v_cmp_ge_f32_e32 vcc, s28, v0
	s_cmp_eq_u64 vcc, exec
	s_cbranch_scc1 .LBB0_2906
	v_max_f32_e32 v0, v0, v0
	v_max_f32_e32 v2, 0, v0
	v_exp_f32_e64 v0, -v2
	v_add_f32_e32 v181, v181, v2
	v_sub_f32_e32 v111, v111, v2
	v_sub_f32_e32 v110, v110, v2
	v_pk_mul_f32 v[78:79], v[78:79], v[0:1] op_sel_hi:[1,0]
	v_pk_mul_f32 v[76:77], v[76:77], v[0:1] op_sel_hi:[1,0]
	v_pk_mul_f32 v[74:75], v[74:75], v[0:1] op_sel_hi:[1,0]
	v_pk_mul_f32 v[72:73], v[72:73], v[0:1] op_sel_hi:[1,0]
	v_pk_mul_f32 v[70:71], v[70:71], v[0:1] op_sel_hi:[1,0]
	v_pk_mul_f32 v[68:69], v[68:69], v[0:1] op_sel_hi:[1,0]
	v_pk_mul_f32 v[66:67], v[66:67], v[0:1] op_sel_hi:[1,0]
	v_pk_mul_f32 v[64:65], v[64:65], v[0:1] op_sel_hi:[1,0]
	v_pk_mul_f32 v[62:63], v[62:63], v[0:1] op_sel_hi:[1,0]
	v_pk_mul_f32 v[60:61], v[60:61], v[0:1] op_sel_hi:[1,0]
	v_pk_mul_f32 v[58:59], v[58:59], v[0:1] op_sel_hi:[1,0]
	v_pk_mul_f32 v[56:57], v[56:57], v[0:1] op_sel_hi:[1,0]
	v_pk_mul_f32 v[54:55], v[54:55], v[0:1] op_sel_hi:[1,0]
	v_pk_mul_f32 v[52:53], v[52:53], v[0:1] op_sel_hi:[1,0]
	v_pk_mul_f32 v[50:51], v[50:51], v[0:1] op_sel_hi:[1,0]
	v_pk_mul_f32 v[48:49], v[48:49], v[0:1] op_sel_hi:[1,0]
	v_pk_mul_f32 v[46:47], v[46:47], v[0:1] op_sel_hi:[1,0]
	v_pk_mul_f32 v[44:45], v[44:45], v[0:1] op_sel_hi:[1,0]
	v_pk_mul_f32 v[42:43], v[42:43], v[0:1] op_sel_hi:[1,0]
	v_pk_mul_f32 v[40:41], v[40:41], v[0:1] op_sel_hi:[1,0]
	v_pk_mul_f32 v[38:39], v[38:39], v[0:1] op_sel_hi:[1,0]
	v_pk_mul_f32 v[36:37], v[36:37], v[0:1] op_sel_hi:[1,0]
	v_pk_mul_f32 v[34:35], v[34:35], v[0:1] op_sel_hi:[1,0]
	v_pk_mul_f32 v[32:33], v[32:33], v[0:1] op_sel_hi:[1,0]
	v_pk_mul_f32 v[30:31], v[30:31], v[0:1] op_sel_hi:[1,0]
	v_pk_mul_f32 v[28:29], v[28:29], v[0:1] op_sel_hi:[1,0]
	v_pk_mul_f32 v[26:27], v[26:27], v[0:1] op_sel_hi:[1,0]
	v_pk_mul_f32 v[24:25], v[24:25], v[0:1] op_sel_hi:[1,0]
	v_pk_mul_f32 v[22:23], v[22:23], v[0:1] op_sel_hi:[1,0]
	v_pk_mul_f32 v[20:21], v[20:21], v[0:1] op_sel_hi:[1,0]
	v_pk_mul_f32 v[18:19], v[18:19], v[0:1] op_sel_hi:[1,0]
	v_pk_mul_f32 v[16:17], v[16:17], v[0:1] op_sel_hi:[1,0]
	v_sub_f32_e32 v109, v109, v2
	v_sub_f32_e32 v108, v108, v2
	v_sub_f32_e32 v107, v107, v2
	v_sub_f32_e32 v106, v106, v2
	v_sub_f32_e32 v105, v105, v2
	v_sub_f32_e32 v104, v104, v2
	v_sub_f32_e32 v103, v103, v2
	v_sub_f32_e32 v102, v102, v2
	v_sub_f32_e32 v101, v101, v2
	v_sub_f32_e32 v100, v100, v2
	v_sub_f32_e32 v99, v99, v2
	v_sub_f32_e32 v98, v98, v2
	v_sub_f32_e32 v97, v97, v2
	v_sub_f32_e32 v96, v96, v2
	v_sub_f32_e32 v95, v95, v2
	v_sub_f32_e32 v94, v94, v2
	v_sub_f32_e32 v93, v93, v2
	v_sub_f32_e32 v92, v92, v2
	v_sub_f32_e32 v91, v91, v2
	v_sub_f32_e32 v90, v90, v2
	v_sub_f32_e32 v89, v89, v2
	v_sub_f32_e32 v88, v88, v2
	v_sub_f32_e32 v87, v87, v2
	v_sub_f32_e32 v86, v86, v2
	v_sub_f32_e32 v85, v85, v2
	v_sub_f32_e32 v84, v84, v2
	v_sub_f32_e32 v83, v83, v2
	v_sub_f32_e32 v82, v82, v2
	v_sub_f32_e32 v81, v81, v2
	v_sub_f32_e32 v80, v80, v2
	v_mul_f32_e32 v171, v171, v0
